# DA: next unit T5 bucket lookup issued before the K/V prefetch so its wait no longer drains the prefetch (plus earlier EpiUp/HG3 edits)
# speedup vs baseline: 1.0075x; 1.0026x over previous
; DI f32x4 mfma32(bf16x8 a, bf16x8 b, f32x4 c) { return __builtin_amdgcn_mfma_f32_16x16x32_bf16(a, b, c, 0, 0, 0); }
; #define DA_DECODE(UNIT) do { cfg = (UNIT) / 512; const int rem_ = (UNIT) % 512; h = rem_ >> 7; const int blk_ = rem_ & 127; d = 1 << (2 * cfg); L = Tg / d; const int nb128_ = L / 128, per_seq_ = d * nb128_; \
;         const int s_ = blk_ / per_seq_, r2_ = blk_ % per_seq_; rho = r2_ / nb128_; u0 = (r2_ % nb128_) * 128; seq0 = s_ * Tg; } while (0)
; DI void phase_da(const Ctx& c, LAS unsigned char* lds, int g, const bf16* PROJ, bf16* DAO, float* DALSE, int bid, int nb, int tid) {
;     ...
;         for (int tt = 0; tt < 9; ++tt) { f32x4 sv = {0.f, 0.f, 0.f, 0.f}; sv = mfma32(ld_contig(Kimg, 72, (w + tt) * 16, 0, lane), qf0, sv); sv = mfma32(ld_contig(Kimg, 72, (w + tt) * 16, 32, lane), qf1, sv); sc[tt] = sv; }
;         __builtin_amdgcn_sched_barrier(0);
;         const bool has_next = iu + wpx < UPX;
;         if (has_next) { DA_DECODE(xcd * UPX + iu + wpx); DA_LOAD(); }
.LBB0_238:
	s_and_b32 s1, s41, 1
	s_mul_i32 s8, s1, 0x122c0
	s_add_i32 s45, s8, 0
	v_add3_u32 v1, s45, v103, v136
	ds_read_b128 v[46:49], v1 offset:36864
	ds_read_b128 v[50:53], v1 offset:36928
	v_add3_u32 v1, s45, v105, v136
	s_waitcnt vmcnt(5) lgkmcnt(1)
	v_mfma_f32_16x16x32_bf16 v[46:49], v[46:49], v[6:9], 0
	s_waitcnt vmcnt(4) lgkmcnt(0)
	v_mfma_f32_16x16x32_bf16 v[62:65], v[50:53], v[10:13], v[46:49]
	ds_read_b128 v[50:53], v1 offset:36928
	s_nop 4
	ds_read_b128 v[46:49], v1 offset:36864
	v_add3_u32 v1, s45, v107, v136
	s_waitcnt lgkmcnt(0)
	v_mfma_f32_16x16x32_bf16 v[46:49], v[46:49], v[6:9], 0
	v_mfma_f32_16x16x32_bf16 v[78:81], v[50:53], v[10:13], v[46:49]
	ds_read_b128 v[50:53], v1 offset:36928
	s_nop 5
	ds_read_b128 v[46:49], v1 offset:36864
	s_waitcnt lgkmcnt(0)
	v_mfma_f32_16x16x32_bf16 v[46:49], v[46:49], v[6:9], 0
	v_add3_u32 v1, s45, v109, v136
	v_mfma_f32_16x16x32_bf16 v[74:77], v[50:53], v[10:13], v[46:49]
	ds_read_b128 v[50:53], v1 offset:36928
	s_nop 4
	ds_read_b128 v[46:49], v1 offset:36864
	s_waitcnt lgkmcnt(0)
	v_mfma_f32_16x16x32_bf16 v[46:49], v[46:49], v[6:9], 0
	v_add3_u32 v1, s45, v111, v136
	v_mfma_f32_16x16x32_bf16 v[70:73], v[50:53], v[10:13], v[46:49]
	ds_read_b128 v[50:53], v1 offset:36928
	s_nop 4
	ds_read_b128 v[46:49], v1 offset:36864
	s_waitcnt lgkmcnt(0)
	v_mfma_f32_16x16x32_bf16 v[46:49], v[46:49], v[6:9], 0
	v_add3_u32 v1, s45, v113, v136
	v_mfma_f32_16x16x32_bf16 v[66:69], v[50:53], v[10:13], v[46:49]
	ds_read_b128 v[50:53], v1 offset:36928
	s_nop 4
	ds_read_b128 v[46:49], v1 offset:36864
	s_waitcnt lgkmcnt(0)
	v_mfma_f32_16x16x32_bf16 v[46:49], v[46:49], v[6:9], 0
	v_add3_u32 v1, s45, v115, v136
	v_mfma_f32_16x16x32_bf16 v[58:61], v[50:53], v[10:13], v[46:49]
	ds_read_b128 v[50:53], v1 offset:36928
	s_nop 4
	ds_read_b128 v[46:49], v1 offset:36864
	s_waitcnt lgkmcnt(0)
	v_mfma_f32_16x16x32_bf16 v[46:49], v[46:49], v[6:9], 0
	v_add3_u32 v1, s45, v117, v136
	ds_read_b128 v[54:57], v1 offset:36928
	v_mfma_f32_16x16x32_bf16 v[50:53], v[50:53], v[10:13], v[46:49]
	s_nop 4
	ds_read_b128 v[46:49], v1 offset:36864
	s_waitcnt lgkmcnt(0)
	v_mfma_f32_16x16x32_bf16 v[46:49], v[46:49], v[6:9], 0
	v_add3_u32 v1, s45, v119, v136
	ds_read_b128 v[90:93], v1 offset:36928
	v_mfma_f32_16x16x32_bf16 v[54:57], v[54:57], v[10:13], v[46:49]
	s_nop 4
	ds_read_b128 v[46:49], v1 offset:36864
	s_waitcnt lgkmcnt(0)
	v_mfma_f32_16x16x32_bf16 v[46:49], v[46:49], v[6:9], 0
	v_mfma_f32_16x16x32_bf16 v[46:49], v[90:93], v[10:13], v[46:49]
	s_cmp_lt_i32 s42, s38
	s_cselect_b64 s[14:15], -1, 0
	s_cmp_ge_i32 s42, s38
	s_cbranch_scc1 .LBB0_252
	s_add_i32 s8, s39, s42
	s_ashr_i32 s9, s8, 31
	s_lshr_b32 s9, s9, 23
	s_add_i32 s9, s8, s9
	s_ashr_i32 s18, s9, 9
	s_lshl_b32 s47, s18, 1
	s_lshr_b32 s19, s57, s47
	s_lshr_b32 s35, s19, 7
	s_lshl_b32 s34, s35, s47
	s_abs_i32 s36, s34
	v_cvt_f32_u32_e32 v1, s36
	s_sub_i32 s37, 0, s36
	s_and_b32 s9, s9, 0xfffffe00
	s_sub_i32 s8, s8, s9
	v_rcp_iflag_f32_e32 v1, v1
	s_ashr_i32 s34, s8, 7
	v_mov_b32_e32 v245, 0x81
	v_mad_i64_i32 v[246:247], vcc, s18, v245, v[84:85]
	s_and_b64 s[100:101], s[2:3], s[4:5]
	s_and_saveexec_b64 s[98:99], s[100:101]
	global_load_ubyte v244, v[246:247], off offset:-16
	s_mov_b64 exec, s[98:99]
	s_and_b32 s8, s8, 0x7f
	s_lshr_b32 s9, s8, s58
	v_mul_f32_e32 v1, 0x4f7ffffe, v1
	v_cvt_u32_f32_e32 v1, v1
	v_mov_b32_e32 v89, v0
	v_mov_b32_e32 v16, v0
	v_mov_b32_e32 v17, v0
	v_readfirstlane_b32 s43, v1
	s_mul_i32 s37, s37, s43
	s_mul_hi_u32 s37, s43, s37
	s_add_i32 s43, s43, s37
	s_mul_hi_u32 s37, s8, s43
	s_mul_i32 s37, s37, s36
	s_sub_i32 s8, s8, s37
	s_sub_i32 s37, s8, s36
	s_cmp_ge_u32 s8, s36
	s_cselect_b32 s8, s37, s8
	s_sub_i32 s37, s8, s36
	s_cmp_ge_u32 s8, s36
	s_cselect_b32 s8, s37, s8
	s_sub_i32 s36, s50, s47
	s_add_i32 s37, s35, -1
	s_lshr_b32 s35, s8, s36
	s_and_b32 s8, s8, s37
	s_lshl_b32 s43, s8, 7
	s_lshl_b32 s44, s9, s59
	v_add_u32_e32 v1, s43, v98
	v_lshlrev_b32_e32 v1, s47, v1
	s_or_b32 s36, s35, s44
	v_add_u32_e32 v2, s36, v1
	v_ashrrev_i32_e32 v3, 31, v2
	s_lshl_b32 s8, s34, 6
	v_lshlrev_b64 v[2:3], 13, v[2:3]
	s_ashr_i32 s9, s8, 31
	v_lshl_add_u64 v[2:3], s[82:83], 0, v[2:3]
	s_lshl_b64 s[8:9], s[8:9], 1
	v_lshl_add_u64 v[2:3], v[2:3], 0, s[8:9]
	v_lshl_add_u64 v[2:3], v[2:3], 0, v[88:89]
	s_and_saveexec_b64 s[98:99], s[2:3]
	s_cbranch_execz .Lda_t5_done
	v_mov_b32_e32 v96, 0xf149f2ca
	s_and_b64 exec, exec, s[4:5]
	s_waitcnt vmcnt(0)
	v_lshl_add_u32 v248, v244, 2, s34
	v_ashrrev_i32_e32 v249, 31, v248
	v_lshl_add_u64 v[248:249], v[248:249], 2, s[66:67]
	global_load_dword v96, v[248:249], off
.Lda_t5_done:
	s_mov_b64 exec, s[98:99]
	global_load_dwordx4 v[6:9], v[2:3], off offset:1536
	global_load_dwordx4 v[10:13], v[2:3], off offset:1600
	s_sub_i32 s37, s43, 64
	v_add_u32_e32 v1, s37, v5
	v_mov_b32_e32 v14, v0
	v_mov_b32_e32 v15, v0
	v_mov_b64_e32 v[20:21], v[16:17]
	v_mov_b64_e32 v[24:25], v[16:17]
	v_lshl_add_u64 v[90:91], v[82:83], 0, s[8:9]
	v_cmp_gt_u32_e32 vcc, s19, v1
	v_mov_b64_e32 v[18:19], v[14:15]
	v_mov_b64_e32 v[22:23], v[14:15]
	s_and_saveexec_b64 s[8:9], vcc
	s_cbranch_execz .LBB0_241
	v_lshlrev_b32_e32 v1, s47, v1
	v_add_u32_e32 v2, s36, v1
	v_ashrrev_i32_e32 v3, 31, v2
	v_lshlrev_b64 v[2:3], 13, v[2:3]
	v_lshl_add_u64 v[2:3], v[90:91], 0, v[2:3]
	global_load_dwordx4 v[18:21], v[2:3], off offset:2560
	global_load_dwordx4 v[22:25], v[2:3], off offset:2048

.LBB0_250:
.LBB0_251:
	s_or_b64 exec, exec, s[8:9]
	s_lshl_b32 s36, 1, s47
	s_branch .LBB0_253
